# attention LDS-DMA addressing moved to SGPR bases + 32-bit lane offsets (saddr form): 12 v_lshl_add_u64 per tile removed; on top of no-setprio + pipelined mem-attention reads
# baseline (speedup 1.0000x reference)
; __device__ __forceinline__ int v_rd_base(int lane) { return ((lane & 3) << 3) | (((lane >> 2) & 3) << 6) | (((lane >> 4) & 1) << 5) | (((lane >> 5) & 1) << 8); }
; template <int LD>
; __device__ __forceinline__ void attn256_body(const bf16_t* __restrict__ Qb, const bf16_t* __restrict__ Kh, const unsigned char* __restrict__ Vimg, int seq, char* lds, LAS unsigned char* ldsl,
;                                              f32x16 (&o)[8], float (&rli)[16]) {
;     ...
;   for (int d = 0; d < 8; ++d) o[d] = f32x16{};
;   const bf16_t* Qw = Qb + (size_t)(wid * 32 + r32) * LD + hi * 8;
; #pragma unroll
;   for (int d0 = 0; d0 < 8; ++d0) qr[d0] = *(const bf16x8*)(Qw + d0 * 16);
;   unsigned voffK[2], voffV[2];
; #pragma unroll
;   for (int i = 0; i < 2; ++i) { const int b = (i * 512 + tid) * 16;
;     { const int row = b >> 8, cB = (b & 255) ^ ((row & 7) << 4); voffK[i] = (unsigned)(row * LD) * 2u + (unsigned)cB; }
;     { const int st = b >> 9, w = b & 511, kk = (st >> 2) * 8 + (w >> 6), c = (st & 3) * 32 + ((w & 63) >> 1);
;       (void)kk; (void)c; voffV[i] = (unsigned)tid * 16u; } }
;   const unsigned ldsw = (unsigned)wid * 1024u;
;     ...
;   const int NT = seq / 64;
;   const int vb0 = (int)(uintptr_t)lds + 16384 + v_rd_base(lane);
;   const int kbase = (int)(uintptr_t)lds + r32 * 256;
;   constexpr float C = ATT_SCALE * LOG2E;
;   __syncthreads();
;   A2_DMA(0, 0);
;   asm volatile("s_waitcnt vmcnt(0)" ::: "memory"); __syncthreads();
;   if (wid >= 4) __builtin_amdgcn_s_setprio(1);
;   for (int j = 0; j < NT; ++j) {
;     const int cur = j & 1;
;     if (j + 1 < NT) { if (cur) A2_DMA(0, (j + 1) * 64); else A2_DMA(1, (j + 1) * 64); }
.LBB0_661:
	s_lshl_b32 s85, s4, 8
	s_and_b32 s4, s64, 7
	s_lshl_b32 s10, s4, 23
	s_lshl_b32 s36, s4, 9
	s_and_b32 s4, s5, 0x3fffffc0
	s_lshl_b32 s4, s4, 2
	s_add_i32 s53, s4, 0
	v_and_b32_e32 v10, 63, v3
	s_add_i32 s53, s53, 0x24000
	v_and_b32_e32 v13, 7, v3
	v_bitop3_b32 v3, v2, v3, 7 bitop3:0x78
	v_bitop3_b32 v8, v8, v7, s91 bitop3:0x6c
	v_bitop3_b32 v7, v9, v7, s91 bitop3:0x6c
	v_lshlrev_b32_e32 v11, 1, v10
	s_cmp_lg_u32 0, -1
	v_lshlrev_b32_e32 v233, 4, v3
	v_bitop3_b32 v3, v2, v13, 2 bitop3:0x36
	v_lshlrev_b32_e32 v9, 4, v10
	v_lshlrev_b32_e32 v12, 3, v10
	v_and_b32_e32 v11, 32, v11
	s_mov_b32 s45, 0
	s_cselect_b32 s4, 0, 0
	v_lshlrev_b32_e32 v234, 4, v3
	v_bitop3_b32 v3, v2, v13, 4 bitop3:0x36
	v_bitop3_b32 v2, v2, v13, 6 bitop3:0x36
	s_movk_i32 s5, 0x118
	v_mov_b32_e32 v222, v0
	s_or_b32 s44, s36, 0xa901100
	s_add_u32 s98, s80, s44
	s_addc_u32 s99, s81, s45
	s_add_u32 s100, s80, s10
	s_addc_u32 s101, s81, s11
	s_add_u32 s100, s100, 0x1a808000
	s_addc_u32 s101, s101, 0
	v_add_u32_e32 v0, v7, v6
	v_and_b32_e32 v9, 0xc0, v9
	v_lshl_add_u32 v221, v4, 8, s4
	v_lshlrev_b32_e32 v236, 4, v2
	v_and_or_b32 v2, v12, s5, v11
	s_addk_i32 s4, 0x4000
	v_mov_b32_e32 v224, v0
	v_add_u32_e32 v0, v8, v5
	v_mov_b32_e32 v14, v1
	v_mov_b32_e32 v15, v1
	v_cmp_gt_u32_e64 s[38:39], 32, v10
	v_lshl_add_u32 v219, v4, 2, s53
	v_lshlrev_b32_e32 v235, 4, v3
	v_add3_u32 v237, v9, s4, v2
	v_mov_b32_e32 v226, v0
	v_mov_b32_e32 v0, v1
	v_mov_b32_e32 v2, v1
	v_mov_b32_e32 v3, v1
	v_mov_b32_e32 v4, v1
	v_mov_b32_e32 v5, v1
	v_mov_b32_e32 v6, v1
	v_mov_b32_e32 v7, v1
	v_mov_b32_e32 v8, v1
	v_mov_b32_e32 v9, v1
	v_mov_b32_e32 v10, v1
	v_mov_b32_e32 v11, v1
	v_mov_b32_e32 v12, v1
	v_mov_b32_e32 v13, v1
	v_mov_b64_e32 v[30:31], v[14:15]
	v_mov_b64_e32 v[46:47], v[14:15]
	v_mov_b64_e32 v[62:63], v[14:15]
	v_mov_b64_e32 v[78:79], v[14:15]
	v_mov_b64_e32 v[94:95], v[14:15]
	v_mov_b64_e32 v[110:111], v[14:15]
	v_mov_b64_e32 v[126:127], v[14:15]
	v_mov_b64_e32 v[142:143], v[14:15]
	s_mov_b32 s37, s11
	s_add_i32 s56, s0, 0xc000
	s_add_i32 s57, s0, 0x10000
	s_add_i32 s60, s0, 0x12000
	s_add_i32 s61, s0, 0x14000
	s_add_i32 s62, s0, 0x16000
	v_mov_b32_e32 v239, 0
	v_mov_b32_e32 v238, 0xf149f2ca
	v_mov_b64_e32 v[28:29], v[12:13]
	v_mov_b64_e32 v[26:27], v[10:11]
	v_mov_b64_e32 v[24:25], v[8:9]
	v_mov_b64_e32 v[22:23], v[6:7]
	v_mov_b64_e32 v[20:21], v[4:5]
	v_mov_b64_e32 v[18:19], v[2:3]
	v_mov_b64_e32 v[16:17], v[0:1]
	v_mov_b64_e32 v[44:45], v[12:13]
	v_mov_b64_e32 v[42:43], v[10:11]
	v_mov_b64_e32 v[40:41], v[8:9]
	v_mov_b64_e32 v[38:39], v[6:7]
	v_mov_b64_e32 v[36:37], v[4:5]
	v_mov_b64_e32 v[34:35], v[2:3]
	v_mov_b64_e32 v[32:33], v[0:1]
	v_mov_b64_e32 v[60:61], v[12:13]
	v_mov_b64_e32 v[58:59], v[10:11]
	v_mov_b64_e32 v[56:57], v[8:9]
	v_mov_b64_e32 v[54:55], v[6:7]
	v_mov_b64_e32 v[52:53], v[4:5]
	v_mov_b64_e32 v[50:51], v[2:3]
	v_mov_b64_e32 v[48:49], v[0:1]
	v_mov_b64_e32 v[76:77], v[12:13]
	v_mov_b64_e32 v[74:75], v[10:11]
	v_mov_b64_e32 v[72:73], v[8:9]
	v_mov_b64_e32 v[70:71], v[6:7]
	v_mov_b64_e32 v[68:69], v[4:5]
	v_mov_b64_e32 v[66:67], v[2:3]
	v_mov_b64_e32 v[64:65], v[0:1]
	v_mov_b64_e32 v[92:93], v[12:13]
	v_mov_b64_e32 v[90:91], v[10:11]
	v_mov_b64_e32 v[88:89], v[8:9]
	v_mov_b64_e32 v[86:87], v[6:7]
	v_mov_b64_e32 v[84:85], v[4:5]
	v_mov_b64_e32 v[82:83], v[2:3]
	v_mov_b64_e32 v[80:81], v[0:1]
	v_mov_b64_e32 v[108:109], v[12:13]
	v_mov_b64_e32 v[106:107], v[10:11]
	v_mov_b64_e32 v[104:105], v[8:9]
	v_mov_b64_e32 v[102:103], v[6:7]
	v_mov_b64_e32 v[100:101], v[4:5]
	v_mov_b64_e32 v[98:99], v[2:3]
	v_mov_b64_e32 v[96:97], v[0:1]
	v_mov_b64_e32 v[124:125], v[12:13]
	v_mov_b64_e32 v[122:123], v[10:11]
	v_mov_b64_e32 v[120:121], v[8:9]
	v_mov_b64_e32 v[118:119], v[6:7]
	v_mov_b64_e32 v[116:117], v[4:5]
	v_mov_b64_e32 v[114:115], v[2:3]
	v_mov_b64_e32 v[112:113], v[0:1]
	v_mov_b64_e32 v[140:141], v[12:13]
	v_mov_b64_e32 v[138:139], v[10:11]
	v_mov_b64_e32 v[136:137], v[8:9]
	v_mov_b64_e32 v[134:135], v[6:7]
	v_mov_b64_e32 v[132:133], v[4:5]
	v_mov_b64_e32 v[130:131], v[2:3]
	v_mov_b64_e32 v[128:129], v[0:1]
	s_and_b32 s4, s45, 1
	s_cmpk_eq_i32 s45, 0xff
	s_cbranch_scc1 .LBB0_663
.LBB0_662:
	s_cmp_eq_u32 s4, 0
	s_cselect_b32 m0, s56, s0
	s_cselect_b32 s5, s89, 0x2000
	s_cselect_b32 s6, s57, s1
	s_cselect_b32 s7, s60, s28
	s_cselect_b32 s8, s61, s29
	s_cselect_b32 s9, s62, s52
	global_load_lds_dwordx4 v226, s[98:99]
	s_add_i32 m0, s0, s5
	s_nop 0
	global_load_lds_dwordx4 v224, s[98:99]
	s_mov_b32 m0, s6
	s_add_u32 s98, s98, 0x100000
	s_addc_u32 s99, s99, 0
	global_load_lds_dwordx4 v222, s[100:101]
	s_mov_b32 m0, s7
	s_add_u32 s100, s100, 0x2000
	s_addc_u32 s101, s101, 0
	global_load_lds_dwordx4 v222, s[100:101]
	s_mov_b32 m0, s8
	s_add_u32 s100, s100, 0x2000
	s_addc_u32 s101, s101, 0
	global_load_lds_dwordx4 v222, s[100:101]
	s_mov_b32 m0, s9
	s_add_u32 s100, s100, 0x2000
	s_addc_u32 s101, s101, 0
	global_load_lds_dwordx4 v222, s[100:101]
	s_add_u32 s100, s100, 0x2000
	s_addc_u32 s101, s101, 0

; #define SBAR() __builtin_amdgcn_sched_barrier(0)
; #define LGKM_WAIT8() do { asm volatile("s_waitcnt lgkmcnt(8)" ::: "memory"); SBAR(); } while (0)
; #define LGKM_WAIT0() do { asm volatile("s_waitcnt lgkmcnt(0)" ::: "memory"); SBAR(); } while (0)
; #define EX4(P, B) do { _Pragma("unroll") for (int r_ = (B); r_ < (B) + 4; ++r_) { P[r_] = __builtin_amdgcn_exp2f(fmaf(P[r_], C, mnC)); ps += P[r_]; } } while (0)
; __device__ __forceinline__ void exp_pv256(f32x16 (&o)[8], f32x16& p0, f32x16& p1, int vb, float C, float mnC, float& ps) {
;   VG4 fa, fb; bf16x8 pa, pn;
;   ps = 0.f;
;   EX4(p0, 0); EX4(p0, 4); pa = pk4<0>(p0);
;   asm volatile("s_waitcnt lgkmcnt(0)" ::: "memory"); SBAR();
;   vg4_read<0>(fa, vb); vg4_read<0>(fb, vb + 16384);
;   LGKM_WAIT8(); vg4_mma<0>(o, fa, pa); EX4(p0, 8); SBAR();
;   vg4_read<1>(fa, vb); LGKM_WAIT8(); vg4_mma<1>(o, fb, pa); EX4(p0, 12); pn = pk4<8>(p0); SBAR();
;   vg4_read<1>(fb, vb + 16384); LGKM_WAIT8(); vg4_mma<0>(o, fa, pn); EX4(p1, 0); SBAR();
;   vg4_read<2>(fa, vb); LGKM_WAIT8(); vg4_mma<1>(o, fb, pn); EX4(p1, 4); pa = pk4<0>(p1); SBAR();
;   vg4_read<2>(fb, vb + 16384); LGKM_WAIT8(); vg4_mma<0>(o, fa, pa); EX4(p1, 8); SBAR();
;   vg4_read<3>(fa, vb); LGKM_WAIT8(); vg4_mma<1>(o, fb, pa); EX4(p1, 12); pn = pk4<8>(p1); SBAR();
;   vg4_read<3>(fb, vb + 16384); LGKM_WAIT8(); vg4_mma<0>(o, fa, pn); SBAR();
;   LGKM_WAIT0(); vg4_mma<1>(o, fb, pn);
.LBB0_668:
	v_mul_f32_e32 v14, 0xbe0293ee, v238
	v_fmamk_f32 v2, v160, 0x3e0293ee, v14
	v_exp_f32_e32 v2, v2
	v_fmamk_f32 v3, v161, 0x3e0293ee, v14
	v_exp_f32_e32 v3, v3
	v_fmamk_f32 v4, v162, 0x3e0293ee, v14
	v_exp_f32_e32 v4, v4
	v_fmamk_f32 v5, v163, 0x3e0293ee, v14
	v_exp_f32_e32 v5, v5
	v_fmamk_f32 v7, v164, 0x3e0293ee, v14
	v_add_f32_e32 v6, 0, v2
	v_exp_f32_e32 v7, v7
	v_fmamk_f32 v8, v165, 0x3e0293ee, v14
	v_add_f32_e32 v6, v3, v6
	v_exp_f32_e32 v8, v8
	v_fmamk_f32 v9, v166, 0x3e0293ee, v14
	v_add_f32_e32 v6, v4, v6
	v_exp_f32_e32 v9, v9
	v_fmamk_f32 v10, v167, 0x3e0293ee, v14
	v_add_f32_e32 v6, v5, v6
	v_exp_f32_e32 v10, v10
	v_add_f32_e32 v6, v7, v6
	v_cvt_pk_bf16_f32 v2, v2, v3
	v_cvt_pk_bf16_f32 v3, v4, v5
	v_cvt_pk_bf16_f32 v4, v7, v8
	v_cvt_pk_bf16_f32 v5, v9, v10
	s_waitcnt lgkmcnt(0)
	v_add_f32_e32 v6, v8, v6
	s_add_i32 s45, s45, 1
	v_add_f32_e32 v6, v9, v6
	v_permlane32_swap_b32_e32 v2, v4
	v_add_u32_e32 v15, s4, v237
	v_add_f32_e32 v248, v10, v6
	v_permlane32_swap_b32_e32 v3, v5
	ds_read_b64_tr_b16 v[6:7], v15 offset:0
	ds_read_b64_tr_b16 v[8:9], v15 offset:0x800
	ds_read_b64_tr_b16 v[10:11], v15 offset:0x200
	ds_read_b64_tr_b16 v[12:13], v15 offset:0xa00
	ds_read_b64_tr_b16 v[160:161], v15 offset:0x400
	ds_read_b64_tr_b16 v[162:163], v15 offset:0xc00
	ds_read_b64_tr_b16 v[164:165], v15 offset:0x600
	ds_read_b64_tr_b16 v[166:167], v15 offset:0xe00
	v_add_u32_e32 v249, 0x4000, v15
	ds_read_b64_tr_b16 v[208:209], v249 offset:0
	ds_read_b64_tr_b16 v[210:211], v249 offset:0x800
	ds_read_b64_tr_b16 v[212:213], v249 offset:0x200
	ds_read_b64_tr_b16 v[214:215], v249 offset:0xa00
	ds_read_b64_tr_b16 v[240:241], v249 offset:0x400
	ds_read_b64_tr_b16 v[242:243], v249 offset:0xc00
	ds_read_b64_tr_b16 v[244:245], v249 offset:0x600
	ds_read_b64_tr_b16 v[246:247], v249 offset:0xe00
	s_waitcnt lgkmcnt(8)
	s_nop 0
	v_mfma_f32_32x32x16_bf16 v[128:143], v[2:5], v[6:9], v[128:143]
	v_fmamk_f32 v6, v168, 0x3e0293ee, v14
	v_exp_f32_e32 v168, v6
	v_fmamk_f32 v6, v169, 0x3e0293ee, v14
	v_exp_f32_e32 v169, v6
	v_fmamk_f32 v6, v170, 0x3e0293ee, v14
	v_exp_f32_e32 v170, v6
	v_fmamk_f32 v6, v171, 0x3e0293ee, v14
	v_mfma_f32_32x32x16_bf16 v[112:127], v[2:5], v[10:13], v[112:127]
	v_exp_f32_e32 v171, v6
	v_add_f32_e32 v6, v168, v248
	v_add_f32_e32 v6, v169, v6
	v_add_f32_e32 v6, v170, v6
	v_add_f32_e32 v248, v171, v6
	v_mfma_f32_32x32x16_bf16 v[96:111], v[2:5], v[160:163], v[96:111]
	v_mfma_f32_32x32x16_bf16 v[80:95], v[2:5], v[164:167], v[80:95]
	ds_read_b64_tr_b16 v[6:7], v15 offset:0x1000
	ds_read_b64_tr_b16 v[8:9], v15 offset:0x1800
	ds_read_b64_tr_b16 v[10:11], v15 offset:0x1200
	ds_read_b64_tr_b16 v[12:13], v15 offset:0x1a00
	ds_read_b64_tr_b16 v[160:161], v15 offset:0x1400
	ds_read_b64_tr_b16 v[162:163], v15 offset:0x1c00
	ds_read_b64_tr_b16 v[164:165], v15 offset:0x1600
	ds_read_b64_tr_b16 v[166:167], v15 offset:0x1e00
	s_waitcnt lgkmcnt(8)
	v_mfma_f32_32x32x16_bf16 v[64:79], v[2:5], v[208:211], v[64:79]
	v_fmamk_f32 v172, v172, 0x3e0293ee, v14
	v_exp_f32_e32 v172, v172
	v_fmamk_f32 v173, v173, 0x3e0293ee, v14
	v_exp_f32_e32 v173, v173
	v_fmamk_f32 v174, v174, 0x3e0293ee, v14
	v_exp_f32_e32 v174, v174
	v_fmamk_f32 v175, v175, 0x3e0293ee, v14
	v_mfma_f32_32x32x16_bf16 v[48:63], v[2:5], v[212:215], v[48:63]
	v_exp_f32_e32 v175, v175
	v_add_f32_e32 v208, v172, v248
	v_add_f32_e32 v208, v173, v208
	v_add_f32_e32 v208, v174, v208
	v_cvt_pk_bf16_f32 v168, v168, v169
	v_cvt_pk_bf16_f32 v169, v170, v171
	v_cvt_pk_bf16_f32 v170, v172, v173
	v_mfma_f32_32x32x16_bf16 v[32:47], v[2:5], v[240:243], v[32:47]
	v_cvt_pk_bf16_f32 v171, v174, v175
	v_add_f32_e32 v248, v175, v208
	v_permlane32_swap_b32_e32 v168, v170
	v_permlane32_swap_b32_e32 v169, v171
	v_mfma_f32_32x32x16_bf16 v[16:31], v[2:5], v[244:247], v[16:31]
	ds_read_b64_tr_b16 v[2:3], v249 offset:0x1000
	ds_read_b64_tr_b16 v[4:5], v249 offset:0x1800
	ds_read_b64_tr_b16 v[172:173], v249 offset:0x1200
	ds_read_b64_tr_b16 v[174:175], v249 offset:0x1a00
	ds_read_b64_tr_b16 v[208:209], v249 offset:0x1400
	ds_read_b64_tr_b16 v[210:211], v249 offset:0x1c00
	ds_read_b64_tr_b16 v[212:213], v249 offset:0x1600
	ds_read_b64_tr_b16 v[214:215], v249 offset:0x1e00
	s_waitcnt lgkmcnt(8)
	s_nop 0
	v_mfma_f32_32x32x16_bf16 v[128:143], v[168:171], v[6:9], v[128:143]
	v_fmamk_f32 v6, v144, 0x3e0293ee, v14
	v_exp_f32_e32 v240, v6
	v_fmamk_f32 v6, v145, 0x3e0293ee, v14
	v_exp_f32_e32 v241, v6
	v_fmamk_f32 v6, v146, 0x3e0293ee, v14
	v_exp_f32_e32 v242, v6
	v_fmamk_f32 v6, v147, 0x3e0293ee, v14
	v_mfma_f32_32x32x16_bf16 v[112:127], v[168:171], v[10:13], v[112:127]
	v_exp_f32_e32 v243, v6
	v_add_f32_e32 v6, v240, v248
	v_add_f32_e32 v6, v241, v6
	v_add_f32_e32 v6, v242, v6
	v_add_f32_e32 v244, v243, v6
	v_mfma_f32_32x32x16_bf16 v[96:111], v[168:171], v[160:163], v[96:111]
	v_mfma_f32_32x32x16_bf16 v[80:95], v[168:171], v[164:167], v[80:95]
	ds_read_b64_tr_b16 v[6:7], v15 offset:0x2000
	ds_read_b64_tr_b16 v[8:9], v15 offset:0x2800
	ds_read_b64_tr_b16 v[10:11], v15 offset:0x2200
	ds_read_b64_tr_b16 v[12:13], v15 offset:0x2a00
	ds_read_b64_tr_b16 v[144:145], v15 offset:0x2400
	ds_read_b64_tr_b16 v[146:147], v15 offset:0x2c00
	ds_read_b64_tr_b16 v[160:161], v15 offset:0x2600
	ds_read_b64_tr_b16 v[162:163], v15 offset:0x2e00
	s_waitcnt lgkmcnt(8)
; #define SBAR() __builtin_amdgcn_sched_barrier(0)
; __device__ __forceinline__ float half_swap_sum(float v) { auto rr = __builtin_amdgcn_permlane32_swap(__float_as_uint(v), __float_as_uint(v), false, false); return __uint_as_float(rr[0]) + __uint_as_float(rr[1]); }
; #define LGKM_WAIT8() do { asm volatile("s_waitcnt lgkmcnt(8)" ::: "memory"); SBAR(); } while (0)
; #define LGKM_WAIT0() do { asm volatile("s_waitcnt lgkmcnt(0)" ::: "memory"); SBAR(); } while (0)
; #define EX4(P, B) do { _Pragma("unroll") for (int r_ = (B); r_ < (B) + 4; ++r_) { P[r_] = __builtin_amdgcn_exp2f(fmaf(P[r_], C, mnC)); ps += P[r_]; } } while (0)
; __device__ __forceinline__ void exp_pv256(f32x16 (&o)[8], f32x16& p0, f32x16& p1, int vb, float C, float mnC, float& ps) {
;     ...
;   vg4_read<1>(fa, vb); LGKM_WAIT8(); vg4_mma<1>(o, fb, pa); EX4(p0, 12); pn = pk4<8>(p0); SBAR();
;   vg4_read<1>(fb, vb + 16384); LGKM_WAIT8(); vg4_mma<0>(o, fa, pn); EX4(p1, 0); SBAR();
;   vg4_read<2>(fa, vb); LGKM_WAIT8(); vg4_mma<1>(o, fb, pn); EX4(p1, 4); pa = pk4<0>(p1); SBAR();
;   vg4_read<2>(fb, vb + 16384); LGKM_WAIT8(); vg4_mma<0>(o, fa, pa); EX4(p1, 8); SBAR();
;   vg4_read<3>(fa, vb); LGKM_WAIT8(); vg4_mma<1>(o, fb, pa); EX4(p1, 12); pn = pk4<8>(p1); SBAR();
;   vg4_read<3>(fb, vb + 16384); LGKM_WAIT8(); vg4_mma<0>(o, fa, pn); SBAR();
;   LGKM_WAIT0(); vg4_mma<1>(o, fb, pn);
; template <int LD>
; __device__ __forceinline__ void attn256_body(const bf16_t* __restrict__ Qb, const bf16_t* __restrict__ Kh, const unsigned char* __restrict__ Vimg, int seq, char* lds, LAS unsigned char* ldsl,
;                                              f32x16 (&o)[8], float (&rli)[16]) {
;     ...
;     ps = half_swap_sum(ps);
;     l_reg = l_reg * alpha + ps;
;     asm volatile("s_waitcnt vmcnt(0)" ::: "memory"); __syncthreads();
	v_mfma_f32_32x32x16_bf16 v[64:79], v[168:171], v[2:5], v[64:79]
	v_fmamk_f32 v2, v148, 0x3e0293ee, v14
	v_exp_f32_e32 v4, v2
	v_fmamk_f32 v2, v149, 0x3e0293ee, v14
	v_exp_f32_e32 v5, v2
	v_fmamk_f32 v2, v150, 0x3e0293ee, v14
	v_exp_f32_e32 v148, v2
	v_fmamk_f32 v2, v151, 0x3e0293ee, v14
	v_mfma_f32_32x32x16_bf16 v[48:63], v[168:171], v[172:175], v[48:63]
	v_exp_f32_e32 v149, v2
	v_add_f32_e32 v2, v4, v244
	v_add_f32_e32 v2, v5, v2
	v_add_f32_e32 v2, v148, v2
	v_add_f32_e32 v244, v149, v2
	v_cvt_pk_bf16_f32 v2, v240, v241
	v_cvt_pk_bf16_f32 v3, v242, v243
	v_mfma_f32_32x32x16_bf16 v[32:47], v[168:171], v[208:211], v[32:47]
	v_cvt_pk_bf16_f32 v4, v4, v5
	v_cvt_pk_bf16_f32 v5, v148, v149
	s_nop 0
	v_permlane32_swap_b32_e32 v2, v4
	v_permlane32_swap_b32_e32 v3, v5
	v_mfma_f32_32x32x16_bf16 v[16:31], v[168:171], v[212:215], v[16:31]
	ds_read_b64_tr_b16 v[148:149], v249 offset:0x2000
	ds_read_b64_tr_b16 v[150:151], v249 offset:0x2800
	ds_read_b64_tr_b16 v[164:165], v249 offset:0x2200
	ds_read_b64_tr_b16 v[166:167], v249 offset:0x2a00
	ds_read_b64_tr_b16 v[168:169], v249 offset:0x2400
	ds_read_b64_tr_b16 v[170:171], v249 offset:0x2c00
	ds_read_b64_tr_b16 v[172:173], v249 offset:0x2600
	ds_read_b64_tr_b16 v[174:175], v249 offset:0x2e00
	s_waitcnt lgkmcnt(8)
	s_nop 0
	v_mfma_f32_32x32x16_bf16 v[128:143], v[2:5], v[6:9], v[128:143]
	v_fmamk_f32 v6, v152, 0x3e0293ee, v14
	v_exp_f32_e32 v208, v6
	v_fmamk_f32 v6, v153, 0x3e0293ee, v14
	v_exp_f32_e32 v209, v6
	v_fmamk_f32 v6, v154, 0x3e0293ee, v14
	v_exp_f32_e32 v210, v6
	v_fmamk_f32 v6, v155, 0x3e0293ee, v14
	v_mfma_f32_32x32x16_bf16 v[112:127], v[2:5], v[10:13], v[112:127]
	v_exp_f32_e32 v211, v6
	v_add_f32_e32 v6, v208, v244
	v_add_f32_e32 v6, v209, v6
	v_add_f32_e32 v6, v210, v6
	v_add_f32_e32 v212, v211, v6
	v_mfma_f32_32x32x16_bf16 v[96:111], v[2:5], v[144:147], v[96:111]
	v_mfma_f32_32x32x16_bf16 v[80:95], v[2:5], v[160:163], v[80:95]
	ds_read_b64_tr_b16 v[6:7], v15 offset:0x3000
	ds_read_b64_tr_b16 v[8:9], v15 offset:0x3800
	ds_read_b64_tr_b16 v[10:11], v15 offset:0x3200
	ds_read_b64_tr_b16 v[12:13], v15 offset:0x3a00
	ds_read_b64_tr_b16 v[144:145], v15 offset:0x3400
	ds_read_b64_tr_b16 v[146:147], v15 offset:0x3c00
	ds_read_b64_tr_b16 v[152:153], v15 offset:0x3600
	ds_read_b64_tr_b16 v[154:155], v15 offset:0x3e00
	s_waitcnt lgkmcnt(8)
	v_fmamk_f32 v15, v156, 0x3e0293ee, v14
	v_mfma_f32_32x32x16_bf16 v[64:79], v[2:5], v[148:151], v[64:79]
	v_exp_f32_e32 v15, v15
	v_fmamk_f32 v148, v157, 0x3e0293ee, v14
	v_exp_f32_e32 v150, v148
	v_fmamk_f32 v148, v158, 0x3e0293ee, v14
	v_exp_f32_e32 v151, v148
	v_fmac_f32_e32 v14, 0x3e0293ee, v159
	v_exp_f32_e32 v14, v14
	v_mfma_f32_32x32x16_bf16 v[48:63], v[2:5], v[164:167], v[48:63]
	v_add_f32_e32 v148, v15, v212
	v_add_f32_e32 v148, v150, v148
	v_add_f32_e32 v148, v151, v148
	v_add_f32_e32 v212, v14, v148
	v_cvt_pk_bf16_f32 v148, v208, v209
	v_cvt_pk_bf16_f32 v149, v210, v211
	v_cvt_pk_bf16_f32 v150, v15, v150
	v_mfma_f32_32x32x16_bf16 v[32:47], v[2:5], v[168:171], v[32:47]
	v_cvt_pk_bf16_f32 v151, v151, v14
	v_permlane32_swap_b32_e32 v148, v150
	v_permlane32_swap_b32_e32 v149, v151
	v_mfma_f32_32x32x16_bf16 v[16:31], v[2:5], v[172:175], v[16:31]
	ds_read_b64_tr_b16 v[2:3], v249 offset:0x3000
	ds_read_b64_tr_b16 v[4:5], v249 offset:0x3800
	ds_read_b64_tr_b16 v[156:157], v249 offset:0x3200
	ds_read_b64_tr_b16 v[158:159], v249 offset:0x3a00
	ds_read_b64_tr_b16 v[160:161], v249 offset:0x3400
	ds_read_b64_tr_b16 v[162:163], v249 offset:0x3c00
	ds_read_b64_tr_b16 v[164:165], v249 offset:0x3600
	ds_read_b64_tr_b16 v[166:167], v249 offset:0x3e00
	s_waitcnt lgkmcnt(8)
	s_nop 0
	v_mfma_f32_32x32x16_bf16 v[128:143], v[148:151], v[6:9], v[128:143]
	v_mfma_f32_32x32x16_bf16 v[112:127], v[148:151], v[10:13], v[112:127]
	v_mfma_f32_32x32x16_bf16 v[96:111], v[148:151], v[144:147], v[96:111]
	v_mfma_f32_32x32x16_bf16 v[80:95], v[148:151], v[152:155], v[80:95]
	s_waitcnt lgkmcnt(0)
	v_mfma_f32_32x32x16_bf16 v[64:79], v[148:151], v[2:5], v[64:79]
	v_mov_b32_e32 v2, v212
	s_nop 1
	v_permlane32_swap_b32_e32 v212, v2
	s_waitcnt vmcnt(0)
	v_add_f32_e32 v2, v212, v2
	v_fmac_f32_e32 v2, v239, v0
	v_mfma_f32_32x32x16_bf16 v[48:63], v[148:151], v[156:159], v[48:63]
	s_cmpk_eq_i32 s45, 0x100
	s_waitcnt vmcnt(0) lgkmcnt(0)
	s_barrier
	v_mfma_f32_32x32x16_bf16 v[32:47], v[148:151], v[160:163], v[32:47]
	v_mfma_f32_32x32x16_bf16 v[16:31], v[148:151], v[164:167], v[16:31]
	s_cbranch_scc1 .LBB0_671
	v_mov_b32_e32 v239, v2
	s_and_b32 s4, s45, 1
	s_cmpk_eq_i32 s45, 0xff
	s_cbranch_scc0 .LBB0_662
	s_branch .LBB0_663

; __device__ __forceinline__ int v_rd_base(int lane) { return ((lane & 3) << 3) | (((lane >> 2) & 3) << 6) | (((lane >> 4) & 1) << 5) | (((lane >> 5) & 1) << 8); }
; template <int LD>
; __device__ __forceinline__ void attn256_body(const bf16_t* __restrict__ Qb, const bf16_t* __restrict__ Kh, const unsigned char* __restrict__ Vimg, int seq, char* lds, LAS unsigned char* ldsl,
;                                              f32x16 (&o)[8], float (&rli)[16]) {
;     ...
;   for (int d = 0; d < 8; ++d) o[d] = f32x16{};
;   const bf16_t* Qw = Qb + (size_t)(wid * 32 + r32) * LD + hi * 8;
; #pragma unroll
;   for (int d0 = 0; d0 < 8; ++d0) qr[d0] = *(const bf16x8*)(Qw + d0 * 16);
;   unsigned voffK[2], voffV[2];
; #pragma unroll
;   for (int i = 0; i < 2; ++i) { const int b = (i * 512 + tid) * 16;
;     { const int row = b >> 8, cB = (b & 255) ^ ((row & 7) << 4); voffK[i] = (unsigned)(row * LD) * 2u + (unsigned)cB; }
;     { const int st = b >> 9, w = b & 511, kk = (st >> 2) * 8 + (w >> 6), c = (st & 3) * 32 + ((w & 63) >> 1);
;       (void)kk; (void)c; voffV[i] = (unsigned)tid * 16u; } }
;   const unsigned ldsw = (unsigned)wid * 1024u;
;     ...
;   const int NT = seq / 64;
;   const int vb0 = (int)(uintptr_t)lds + 16384 + v_rd_base(lane);
;   const int kbase = (int)(uintptr_t)lds + r32 * 256;
;   constexpr float C = ATT_SCALE * LOG2E;
;   __syncthreads();
;   A2_DMA(0, 0);
;   asm volatile("s_waitcnt vmcnt(0)" ::: "memory"); __syncthreads();
;   if (wid >= 4) __builtin_amdgcn_s_setprio(1);
;   for (int j = 0; j < NT; ++j) {
;     const int cur = j & 1;
;     if (j + 1 < NT) { if (cur) A2_DMA(0, (j + 1) * 64); else A2_DMA(1, (j + 1) * 64); }
.LBB0_675:
	s_and_b32 s4, s4, 0x3fffffc0
	s_lshl_b32 s4, s4, 2
	s_add_i32 s29, s4, 0
	v_and_b32_e32 v10, 63, v3
	s_add_i32 s29, s29, 0x24000
	v_and_b32_e32 v13, 7, v3
	v_bitop3_b32 v3, v2, v3, 7 bitop3:0x78
	v_bitop3_b32 v8, v8, v7, s91 bitop3:0x6c
	v_lshlrev_b32_e32 v11, 1, v10
	s_cmp_lg_u32 0, -1
	v_lshlrev_b32_e32 v233, 4, v3
	v_bitop3_b32 v3, v2, v13, 2 bitop3:0x36
	v_bitop3_b32 v7, v9, v7, s91 bitop3:0x6c
	v_lshlrev_b32_e32 v9, 4, v10
	v_lshlrev_b32_e32 v12, 3, v10
	v_and_b32_e32 v11, 32, v11
	s_cselect_b32 s4, 0, 0
	v_lshlrev_b32_e32 v234, 4, v3
	v_bitop3_b32 v3, v2, v13, 4 bitop3:0x36
	v_bitop3_b32 v2, v2, v13, 6 bitop3:0x36
	s_movk_i32 s5, 0x118
	v_mov_b32_e32 v222, v0
	s_or_b32 s36, s36, 0xa901000
	s_add_u32 s98, s80, s36
	s_addc_u32 s99, s81, s37
	s_add_u32 s100, s80, s10
	s_addc_u32 s101, s81, s11
	s_add_u32 s100, s100, 0x1a808000
	s_addc_u32 s101, s101, 0
	v_add_u32_e32 v0, v8, v5
	v_and_b32_e32 v9, 0xc0, v9
	v_lshl_add_u32 v221, v4, 8, s4
	v_lshlrev_b32_e32 v236, 4, v2
	v_and_or_b32 v2, v12, s5, v11
	s_addk_i32 s4, 0x4000
	v_mov_b32_e32 v224, v0
	v_add_u32_e32 v0, v7, v6
	v_mov_b32_e32 v14, v1
	v_mov_b32_e32 v15, v1
	v_cmp_gt_u32_e64 s[38:39], 32, v10
	v_lshl_add_u32 v219, v4, 2, s29
	v_lshlrev_b32_e32 v235, 4, v3
	v_add3_u32 v237, v9, s4, v2
	v_mov_b32_e32 v226, v0
	v_mov_b32_e32 v0, v1
	v_mov_b32_e32 v2, v1
	v_mov_b32_e32 v3, v1
	v_mov_b32_e32 v4, v1
	v_mov_b32_e32 v5, v1
	v_mov_b32_e32 v6, v1
	v_mov_b32_e32 v7, v1
	v_mov_b32_e32 v8, v1
	v_mov_b32_e32 v9, v1
	v_mov_b32_e32 v10, v1
	v_mov_b32_e32 v11, v1
	v_mov_b32_e32 v12, v1
	v_mov_b32_e32 v13, v1
	v_mov_b64_e32 v[128:129], v[14:15]
	v_mov_b64_e32 v[112:113], v[14:15]
	v_mov_b64_e32 v[96:97], v[14:15]
	v_mov_b64_e32 v[80:81], v[14:15]
	v_mov_b64_e32 v[64:65], v[14:15]
	v_mov_b64_e32 v[48:49], v[14:15]
	v_mov_b64_e32 v[32:33], v[14:15]
	v_mov_b64_e32 v[126:127], v[12:13]
	v_mov_b64_e32 v[124:125], v[10:11]
	v_mov_b64_e32 v[122:123], v[8:9]
	v_mov_b64_e32 v[120:121], v[6:7]
	v_mov_b64_e32 v[118:119], v[4:5]
	v_mov_b64_e32 v[116:117], v[2:3]
	v_mov_b64_e32 v[114:115], v[0:1]
	v_mov_b64_e32 v[110:111], v[12:13]
	v_mov_b64_e32 v[108:109], v[10:11]
	v_mov_b64_e32 v[106:107], v[8:9]
	v_mov_b64_e32 v[104:105], v[6:7]
	v_mov_b64_e32 v[102:103], v[4:5]
	v_mov_b64_e32 v[100:101], v[2:3]
	v_mov_b64_e32 v[98:99], v[0:1]
	v_mov_b64_e32 v[94:95], v[12:13]
	v_mov_b64_e32 v[92:93], v[10:11]
	v_mov_b64_e32 v[90:91], v[8:9]
	v_mov_b64_e32 v[88:89], v[6:7]
	v_mov_b64_e32 v[86:87], v[4:5]
	v_mov_b64_e32 v[84:85], v[2:3]
	v_mov_b64_e32 v[82:83], v[0:1]
	v_mov_b64_e32 v[78:79], v[12:13]
	v_mov_b64_e32 v[76:77], v[10:11]
	v_mov_b64_e32 v[74:75], v[8:9]
	v_mov_b64_e32 v[72:73], v[6:7]
	v_mov_b64_e32 v[70:71], v[4:5]
	v_mov_b64_e32 v[68:69], v[2:3]
	v_mov_b64_e32 v[66:67], v[0:1]
	v_mov_b64_e32 v[62:63], v[12:13]
	v_mov_b64_e32 v[60:61], v[10:11]
	v_mov_b64_e32 v[58:59], v[8:9]
	v_mov_b64_e32 v[56:57], v[6:7]
	v_mov_b64_e32 v[54:55], v[4:5]
	v_mov_b64_e32 v[52:53], v[2:3]
	v_mov_b64_e32 v[50:51], v[0:1]
	v_mov_b64_e32 v[46:47], v[12:13]
	v_mov_b64_e32 v[44:45], v[10:11]
	v_mov_b64_e32 v[42:43], v[8:9]
	v_mov_b64_e32 v[40:41], v[6:7]
	v_mov_b64_e32 v[38:39], v[4:5]
	v_mov_b64_e32 v[36:37], v[2:3]
	v_mov_b64_e32 v[34:35], v[0:1]
	v_mov_b64_e32 v[30:31], v[12:13]
	v_mov_b64_e32 v[28:29], v[10:11]
	v_mov_b64_e32 v[26:27], v[8:9]
	v_mov_b64_e32 v[24:25], v[6:7]
	v_mov_b64_e32 v[22:23], v[4:5]
	v_mov_b64_e32 v[20:21], v[2:3]
	v_mov_b64_e32 v[18:19], v[0:1]
	v_mov_b64_e32 v[16:17], v[14:15]
	s_mov_b32 s34, 0
	s_add_i32 s35, s0, 0xc000
	s_add_i32 s44, s0, 0x10000
	s_add_i32 s45, s0, 0x12000
	s_add_i32 s48, s0, 0x14000
	s_add_i32 s49, s0, 0x16000
	v_mov_b32_e32 v239, 0
	v_mov_b32_e32 v238, 0xf149f2ca
	v_mov_b64_e32 v[14:15], v[12:13]
	v_mov_b64_e32 v[12:13], v[10:11]
	v_mov_b64_e32 v[10:11], v[8:9]
	v_mov_b64_e32 v[8:9], v[6:7]
	v_mov_b64_e32 v[6:7], v[4:5]
	v_mov_b64_e32 v[4:5], v[2:3]
	v_mov_b64_e32 v[2:3], v[0:1]
	s_and_b32 s4, s34, 1
	s_cmpk_eq_i32 s34, 0xff
	s_cbranch_scc1 .LBB0_677
.LBB0_676:
	s_cmp_eq_u32 s4, 0
	s_cselect_b32 m0, s35, s0
	s_cselect_b32 s5, s89, 0x2000
	s_cselect_b32 s6, s44, s1
	s_cselect_b32 s7, s45, s24
	s_cselect_b32 s8, s48, s25
	s_cselect_b32 s9, s49, s28
	global_load_lds_dwordx4 v224, s[98:99]
	s_add_i32 m0, s0, s5
	s_nop 0
	global_load_lds_dwordx4 v226, s[98:99]
	s_mov_b32 m0, s6
	s_add_u32 s98, s98, 0x100000
	s_addc_u32 s99, s99, 0
	global_load_lds_dwordx4 v222, s[100:101]
	s_mov_b32 m0, s7
	s_add_u32 s100, s100, 0x2000
	s_addc_u32 s101, s101, 0
	global_load_lds_dwordx4 v222, s[100:101]
	s_mov_b32 m0, s8
	s_add_u32 s100, s100, 0x2000
	s_addc_u32 s101, s101, 0
	global_load_lds_dwordx4 v222, s[100:101]
	s_mov_b32 m0, s9
	s_add_u32 s100, s100, 0x2000
	s_addc_u32 s101, s101, 0
	global_load_lds_dwordx4 v222, s[100:101]
	s_add_u32 s100, s100, 0x2000
	s_addc_u32 s101, s101, 0

; #define SBAR() __builtin_amdgcn_sched_barrier(0)
; #define LGKM_WAIT8() do { asm volatile("s_waitcnt lgkmcnt(8)" ::: "memory"); SBAR(); } while (0)
; #define LGKM_WAIT0() do { asm volatile("s_waitcnt lgkmcnt(0)" ::: "memory"); SBAR(); } while (0)
; #define EX4(P, B) do { _Pragma("unroll") for (int r_ = (B); r_ < (B) + 4; ++r_) { P[r_] = __builtin_amdgcn_exp2f(fmaf(P[r_], C, mnC)); ps += P[r_]; } } while (0)
; __device__ __forceinline__ void exp_pv256(f32x16 (&o)[8], f32x16& p0, f32x16& p1, int vb, float C, float mnC, float& ps) {
;   VG4 fa, fb; bf16x8 pa, pn;
;   ps = 0.f;
;   EX4(p0, 0); EX4(p0, 4); pa = pk4<0>(p0);
;   asm volatile("s_waitcnt lgkmcnt(0)" ::: "memory"); SBAR();
;   vg4_read<0>(fa, vb); vg4_read<0>(fb, vb + 16384);
;   LGKM_WAIT8(); vg4_mma<0>(o, fa, pa); EX4(p0, 8); SBAR();
;   vg4_read<1>(fa, vb); LGKM_WAIT8(); vg4_mma<1>(o, fb, pa); EX4(p0, 12); pn = pk4<8>(p0); SBAR();
;   vg4_read<1>(fb, vb + 16384); LGKM_WAIT8(); vg4_mma<0>(o, fa, pn); EX4(p1, 0); SBAR();
;   vg4_read<2>(fa, vb); LGKM_WAIT8(); vg4_mma<1>(o, fb, pn); EX4(p1, 4); pa = pk4<0>(p1); SBAR();
;   vg4_read<2>(fb, vb + 16384); LGKM_WAIT8(); vg4_mma<0>(o, fa, pa); EX4(p1, 8); SBAR();
;   vg4_read<3>(fa, vb); LGKM_WAIT8(); vg4_mma<1>(o, fb, pa); EX4(p1, 12); pn = pk4<8>(p1); SBAR();
;   vg4_read<3>(fb, vb + 16384); LGKM_WAIT8(); vg4_mma<0>(o, fa, pn); SBAR();
;   LGKM_WAIT0(); vg4_mma<1>(o, fb, pn);
.LBB0_682:
	v_mul_f32_e32 v248, 0xbe0293ee, v238
	v_fmamk_f32 v146, v146, 0x3e0293ee, v248
	v_exp_f32_e32 v146, v146
	v_fmamk_f32 v147, v147, 0x3e0293ee, v248
	v_exp_f32_e32 v147, v147
	v_fmamk_f32 v148, v148, 0x3e0293ee, v248
	v_exp_f32_e32 v148, v148
	v_fmamk_f32 v149, v149, 0x3e0293ee, v248
	v_exp_f32_e32 v149, v149
	v_fmamk_f32 v150, v150, 0x3e0293ee, v248
	v_add_f32_e32 v194, 0, v146
	v_exp_f32_e32 v150, v150
	v_fmamk_f32 v151, v151, 0x3e0293ee, v248
	v_add_f32_e32 v194, v147, v194
	v_exp_f32_e32 v151, v151
	v_fmamk_f32 v152, v152, 0x3e0293ee, v248
	v_add_f32_e32 v194, v148, v194
	v_exp_f32_e32 v152, v152
	v_fmamk_f32 v153, v153, 0x3e0293ee, v248
	v_add_f32_e32 v194, v149, v194
	v_exp_f32_e32 v153, v153
	v_add_f32_e32 v194, v150, v194
	v_cvt_pk_bf16_f32 v146, v146, v147
	v_cvt_pk_bf16_f32 v147, v148, v149
	v_cvt_pk_bf16_f32 v148, v150, v151
	v_cvt_pk_bf16_f32 v149, v152, v153
	s_waitcnt lgkmcnt(0)
	v_add_f32_e32 v194, v151, v194
	s_add_i32 s34, s34, 1
	v_add_f32_e32 v194, v152, v194
	v_add_u32_e32 v249, s4, v237
	v_add_f32_e32 v250, v153, v194
	v_permlane32_swap_b32_e32 v146, v148
	v_permlane32_swap_b32_e32 v147, v149
	ds_read_b64_tr_b16 v[150:151], v249 offset:0
	ds_read_b64_tr_b16 v[152:153], v249 offset:0x800
	ds_read_b64_tr_b16 v[194:195], v249 offset:0x200
	ds_read_b64_tr_b16 v[196:197], v249 offset:0xa00
	ds_read_b64_tr_b16 v[198:199], v249 offset:0x400
	ds_read_b64_tr_b16 v[200:201], v249 offset:0xc00
	ds_read_b64_tr_b16 v[202:203], v249 offset:0x600
	ds_read_b64_tr_b16 v[204:205], v249 offset:0xe00
	v_add_u32_e32 v251, 0x4000, v249
	ds_read_b64_tr_b16 v[206:207], v251 offset:0
	ds_read_b64_tr_b16 v[208:209], v251 offset:0x800
	ds_read_b64_tr_b16 v[212:213], v251 offset:0x200
	ds_read_b64_tr_b16 v[214:215], v251 offset:0xa00
	ds_read_b64_tr_b16 v[240:241], v251 offset:0x400
	ds_read_b64_tr_b16 v[242:243], v251 offset:0xc00
	ds_read_b64_tr_b16 v[244:245], v251 offset:0x600
	ds_read_b64_tr_b16 v[246:247], v251 offset:0xe00
	s_waitcnt lgkmcnt(8)
	s_nop 0
	v_mfma_f32_32x32x16_bf16 v[2:17], v[146:149], v[150:153], v[2:17]
	v_fmamk_f32 v150, v154, 0x3e0293ee, v248
	v_exp_f32_e32 v252, v150
	v_fmamk_f32 v150, v155, 0x3e0293ee, v248
	v_exp_f32_e32 v231, v150
	v_fmamk_f32 v150, v156, 0x3e0293ee, v248
	v_exp_f32_e32 v232, v150
	v_fmamk_f32 v150, v157, 0x3e0293ee, v248
	v_mfma_f32_32x32x16_bf16 v[18:33], v[146:149], v[194:197], v[18:33]
	v_exp_f32_e32 v216, v150
	v_add_f32_e32 v150, v252, v250
	v_add_f32_e32 v150, v231, v150
	v_add_f32_e32 v150, v232, v150
	v_add_f32_e32 v217, v216, v150
	v_mfma_f32_32x32x16_bf16 v[34:49], v[146:149], v[198:201], v[34:49]
	v_mfma_f32_32x32x16_bf16 v[50:65], v[146:149], v[202:205], v[50:65]
	ds_read_b64_tr_b16 v[150:151], v249 offset:0x1000
	ds_read_b64_tr_b16 v[152:153], v249 offset:0x1800
	ds_read_b64_tr_b16 v[154:155], v249 offset:0x1200
	ds_read_b64_tr_b16 v[156:157], v249 offset:0x1a00
	ds_read_b64_tr_b16 v[194:195], v249 offset:0x1400
	ds_read_b64_tr_b16 v[196:197], v249 offset:0x1c00
	ds_read_b64_tr_b16 v[198:199], v249 offset:0x1600
	ds_read_b64_tr_b16 v[200:201], v249 offset:0x1e00
	s_waitcnt lgkmcnt(8)
	v_fmamk_f32 v158, v158, 0x3e0293ee, v248
	v_mfma_f32_32x32x16_bf16 v[66:81], v[146:149], v[206:209], v[66:81]
	v_exp_f32_e32 v202, v158
	v_fmamk_f32 v158, v159, 0x3e0293ee, v248
	v_exp_f32_e32 v203, v158
	v_fmamk_f32 v158, v160, 0x3e0293ee, v248
	v_exp_f32_e32 v204, v158
	v_fmamk_f32 v158, v161, 0x3e0293ee, v248
	v_exp_f32_e32 v161, v158
	v_mfma_f32_32x32x16_bf16 v[82:97], v[146:149], v[212:215], v[82:97]
	v_add_f32_e32 v158, v202, v217
	v_add_f32_e32 v158, v203, v158
	v_add_f32_e32 v158, v204, v158
	v_add_f32_e32 v217, v161, v158
	v_cvt_pk_bf16_f32 v158, v252, v231
	v_cvt_pk_bf16_f32 v159, v232, v216
	v_cvt_pk_bf16_f32 v160, v202, v203
	v_mfma_f32_32x32x16_bf16 v[98:113], v[146:149], v[240:243], v[98:113]
	v_cvt_pk_bf16_f32 v161, v204, v161
	v_permlane32_swap_b32_e32 v158, v160
	v_permlane32_swap_b32_e32 v159, v161
	v_mfma_f32_32x32x16_bf16 v[114:129], v[146:149], v[244:247], v[114:129]
	ds_read_b64_tr_b16 v[146:147], v251 offset:0x1000
	ds_read_b64_tr_b16 v[148:149], v251 offset:0x1800
	ds_read_b64_tr_b16 v[202:203], v251 offset:0x1200
	ds_read_b64_tr_b16 v[204:205], v251 offset:0x1a00
	ds_read_b64_tr_b16 v[206:207], v251 offset:0x1400
	ds_read_b64_tr_b16 v[208:209], v251 offset:0x1c00
	ds_read_b64_tr_b16 v[212:213], v251 offset:0x1600
	ds_read_b64_tr_b16 v[214:215], v251 offset:0x1e00
	s_waitcnt lgkmcnt(8)
	s_nop 0
	v_mfma_f32_32x32x16_bf16 v[2:17], v[158:161], v[150:153], v[2:17]
	v_fmamk_f32 v130, v130, 0x3e0293ee, v248
	v_exp_f32_e32 v216, v130
	v_fmamk_f32 v130, v131, 0x3e0293ee, v248
	v_exp_f32_e32 v231, v130
	v_fmamk_f32 v130, v132, 0x3e0293ee, v248
	v_exp_f32_e32 v232, v130
	v_fmamk_f32 v130, v133, 0x3e0293ee, v248
	v_mfma_f32_32x32x16_bf16 v[18:33], v[158:161], v[154:157], v[18:33]
	v_exp_f32_e32 v240, v130
	v_add_f32_e32 v130, v216, v217
	v_add_f32_e32 v130, v231, v130
	v_add_f32_e32 v130, v232, v130
	v_add_f32_e32 v217, v240, v130
	v_mfma_f32_32x32x16_bf16 v[34:49], v[158:161], v[194:197], v[34:49]
	v_mfma_f32_32x32x16_bf16 v[50:65], v[158:161], v[198:201], v[50:65]
	ds_read_b64_tr_b16 v[130:131], v249 offset:0x2000
	ds_read_b64_tr_b16 v[132:133], v249 offset:0x2800
	ds_read_b64_tr_b16 v[150:151], v249 offset:0x2200
	ds_read_b64_tr_b16 v[152:153], v249 offset:0x2a00
	ds_read_b64_tr_b16 v[154:155], v249 offset:0x2400
	ds_read_b64_tr_b16 v[156:157], v249 offset:0x2c00
	ds_read_b64_tr_b16 v[194:195], v249 offset:0x2600
	ds_read_b64_tr_b16 v[196:197], v249 offset:0x2e00
	s_waitcnt lgkmcnt(8)
; #define SBAR() __builtin_amdgcn_sched_barrier(0)
; __device__ __forceinline__ float half_swap_sum(float v) { auto rr = __builtin_amdgcn_permlane32_swap(__float_as_uint(v), __float_as_uint(v), false, false); return __uint_as_float(rr[0]) + __uint_as_float(rr[1]); }
; #define LGKM_WAIT8() do { asm volatile("s_waitcnt lgkmcnt(8)" ::: "memory"); SBAR(); } while (0)
; #define LGKM_WAIT0() do { asm volatile("s_waitcnt lgkmcnt(0)" ::: "memory"); SBAR(); } while (0)
; #define EX4(P, B) do { _Pragma("unroll") for (int r_ = (B); r_ < (B) + 4; ++r_) { P[r_] = __builtin_amdgcn_exp2f(fmaf(P[r_], C, mnC)); ps += P[r_]; } } while (0)
; __device__ __forceinline__ void exp_pv256(f32x16 (&o)[8], f32x16& p0, f32x16& p1, int vb, float C, float mnC, float& ps) {
;     ...
;   vg4_read<1>(fa, vb); LGKM_WAIT8(); vg4_mma<1>(o, fb, pa); EX4(p0, 12); pn = pk4<8>(p0); SBAR();
;   vg4_read<1>(fb, vb + 16384); LGKM_WAIT8(); vg4_mma<0>(o, fa, pn); EX4(p1, 0); SBAR();
;   vg4_read<2>(fa, vb); LGKM_WAIT8(); vg4_mma<1>(o, fb, pn); EX4(p1, 4); pa = pk4<0>(p1); SBAR();
;   vg4_read<2>(fb, vb + 16384); LGKM_WAIT8(); vg4_mma<0>(o, fa, pa); EX4(p1, 8); SBAR();
;   vg4_read<3>(fa, vb); LGKM_WAIT8(); vg4_mma<1>(o, fb, pa); EX4(p1, 12); pn = pk4<8>(p1); SBAR();
;   vg4_read<3>(fb, vb + 16384); LGKM_WAIT8(); vg4_mma<0>(o, fa, pn); SBAR();
;   LGKM_WAIT0(); vg4_mma<1>(o, fb, pn);
; template <int LD>
; __device__ __forceinline__ void attn256_body(const bf16_t* __restrict__ Qb, const bf16_t* __restrict__ Kh, const unsigned char* __restrict__ Vimg, int seq, char* lds, LAS unsigned char* ldsl,
;                                              f32x16 (&o)[8], float (&rli)[16]) {
;     ...
;     ps = half_swap_sum(ps);
;     l_reg = l_reg * alpha + ps;
;     asm volatile("s_waitcnt vmcnt(0)" ::: "memory"); __syncthreads();
	v_fmamk_f32 v134, v134, 0x3e0293ee, v248
	v_mfma_f32_32x32x16_bf16 v[66:81], v[158:161], v[146:149], v[66:81]
	v_exp_f32_e32 v146, v134
	v_fmamk_f32 v134, v135, 0x3e0293ee, v248
	v_exp_f32_e32 v147, v134
	v_fmamk_f32 v134, v136, 0x3e0293ee, v248
	v_exp_f32_e32 v148, v134
	v_fmamk_f32 v134, v137, 0x3e0293ee, v248
	v_exp_f32_e32 v137, v134
	v_mfma_f32_32x32x16_bf16 v[82:97], v[158:161], v[202:205], v[82:97]
	v_add_f32_e32 v134, v146, v217
	v_add_f32_e32 v134, v147, v134
	v_add_f32_e32 v134, v148, v134
	v_add_f32_e32 v217, v137, v134
	v_cvt_pk_bf16_f32 v134, v216, v231
	v_cvt_pk_bf16_f32 v135, v232, v240
	v_cvt_pk_bf16_f32 v136, v146, v147
	v_mfma_f32_32x32x16_bf16 v[98:113], v[158:161], v[206:209], v[98:113]
	v_cvt_pk_bf16_f32 v137, v148, v137
	v_permlane32_swap_b32_e32 v134, v136
	v_permlane32_swap_b32_e32 v135, v137
	v_mfma_f32_32x32x16_bf16 v[114:129], v[158:161], v[212:215], v[114:129]
	ds_read_b64_tr_b16 v[146:147], v251 offset:0x2000
	ds_read_b64_tr_b16 v[148:149], v251 offset:0x2800
	ds_read_b64_tr_b16 v[158:159], v251 offset:0x2200
	ds_read_b64_tr_b16 v[160:161], v251 offset:0x2a00
	ds_read_b64_tr_b16 v[198:199], v251 offset:0x2400
	ds_read_b64_tr_b16 v[200:201], v251 offset:0x2c00
	ds_read_b64_tr_b16 v[202:203], v251 offset:0x2600
	ds_read_b64_tr_b16 v[204:205], v251 offset:0x2e00
	s_waitcnt lgkmcnt(8)
	s_nop 0
	v_mfma_f32_32x32x16_bf16 v[2:17], v[134:137], v[130:133], v[2:17]
	v_fmamk_f32 v130, v138, 0x3e0293ee, v248
	v_exp_f32_e32 v206, v130
	v_fmamk_f32 v130, v139, 0x3e0293ee, v248
	v_exp_f32_e32 v207, v130
	v_fmamk_f32 v130, v140, 0x3e0293ee, v248
	v_exp_f32_e32 v208, v130
	v_fmamk_f32 v130, v141, 0x3e0293ee, v248
	v_mfma_f32_32x32x16_bf16 v[18:33], v[134:137], v[150:153], v[18:33]
	v_exp_f32_e32 v209, v130
	v_add_f32_e32 v130, v206, v217
	v_add_f32_e32 v130, v207, v130
	v_add_f32_e32 v130, v208, v130
	v_add_f32_e32 v212, v209, v130
	v_mfma_f32_32x32x16_bf16 v[34:49], v[134:137], v[154:157], v[34:49]
	v_mfma_f32_32x32x16_bf16 v[50:65], v[134:137], v[194:197], v[50:65]
	ds_read_b64_tr_b16 v[130:131], v249 offset:0x3000
	ds_read_b64_tr_b16 v[132:133], v249 offset:0x3800
	ds_read_b64_tr_b16 v[138:139], v249 offset:0x3200
	ds_read_b64_tr_b16 v[140:141], v249 offset:0x3a00
	ds_read_b64_tr_b16 v[150:151], v249 offset:0x3400
	ds_read_b64_tr_b16 v[152:153], v249 offset:0x3c00
	ds_read_b64_tr_b16 v[154:155], v249 offset:0x3600
	ds_read_b64_tr_b16 v[156:157], v249 offset:0x3e00
	s_waitcnt lgkmcnt(8)
	v_fmamk_f32 v142, v142, 0x3e0293ee, v248
	v_mfma_f32_32x32x16_bf16 v[66:81], v[134:137], v[146:149], v[66:81]
	v_exp_f32_e32 v146, v142
	v_fmamk_f32 v142, v143, 0x3e0293ee, v248
	v_exp_f32_e32 v147, v142
	v_fmamk_f32 v142, v144, 0x3e0293ee, v248
	v_exp_f32_e32 v148, v142
	v_fmac_f32_e32 v248, 0x3e0293ee, v145
	v_exp_f32_e32 v145, v248
	v_mfma_f32_32x32x16_bf16 v[82:97], v[134:137], v[158:161], v[82:97]
	v_add_f32_e32 v142, v146, v212
	v_add_f32_e32 v142, v147, v142
	v_add_f32_e32 v142, v148, v142
	v_add_f32_e32 v212, v145, v142
	v_cvt_pk_bf16_f32 v142, v206, v207
	v_cvt_pk_bf16_f32 v143, v208, v209
	v_cvt_pk_bf16_f32 v144, v146, v147
	v_mfma_f32_32x32x16_bf16 v[98:113], v[134:137], v[198:201], v[98:113]
	v_cvt_pk_bf16_f32 v145, v148, v145
	v_permlane32_swap_b32_e32 v142, v144
	v_permlane32_swap_b32_e32 v143, v145
	v_mfma_f32_32x32x16_bf16 v[114:129], v[134:137], v[202:205], v[114:129]
	ds_read_b64_tr_b16 v[134:135], v251 offset:0x3000
	ds_read_b64_tr_b16 v[136:137], v251 offset:0x3800
	ds_read_b64_tr_b16 v[146:147], v251 offset:0x3200
	ds_read_b64_tr_b16 v[148:149], v251 offset:0x3a00
	ds_read_b64_tr_b16 v[158:159], v251 offset:0x3400
	ds_read_b64_tr_b16 v[160:161], v251 offset:0x3c00
	ds_read_b64_tr_b16 v[194:195], v251 offset:0x3600
	ds_read_b64_tr_b16 v[196:197], v251 offset:0x3e00
	s_waitcnt lgkmcnt(8)
	s_nop 0
	v_mfma_f32_32x32x16_bf16 v[2:17], v[142:145], v[130:133], v[2:17]
	v_mfma_f32_32x32x16_bf16 v[18:33], v[142:145], v[138:141], v[18:33]
	v_mfma_f32_32x32x16_bf16 v[34:49], v[142:145], v[150:153], v[34:49]
	v_mfma_f32_32x32x16_bf16 v[50:65], v[142:145], v[154:157], v[50:65]
	s_waitcnt lgkmcnt(0)
	v_mfma_f32_32x32x16_bf16 v[66:81], v[142:145], v[134:137], v[66:81]
	v_mov_b32_e32 v130, v212
	s_nop 1
	v_permlane32_swap_b32_e32 v212, v130
	s_waitcnt vmcnt(0)
	v_add_f32_e32 v130, v212, v130
	v_fmac_f32_e32 v130, v239, v0
	v_mfma_f32_32x32x16_bf16 v[82:97], v[142:145], v[146:149], v[82:97]
	s_cmpk_eq_i32 s34, 0x100
	s_waitcnt vmcnt(0) lgkmcnt(0)
	s_barrier
	v_mfma_f32_32x32x16_bf16 v[98:113], v[142:145], v[158:161], v[98:113]
	v_mfma_f32_32x32x16_bf16 v[114:129], v[142:145], v[194:197], v[114:129]
	s_cbranch_scc1 .LBB0_685
	v_mov_b32_e32 v239, v130
	s_and_b32 s4, s34, 1
	s_cmpk_eq_i32 s34, 0xff
	s_cbranch_scc0 .LBB0_676
	s_branch .LBB0_677

; __global__ void __launch_bounds__(512, 2) mega(Params P) {
;   extern __shared__ __attribute__((aligned(16))) unsigned char shm[];
	.amdhsa_kernel _Z4mega6Params
		.amdhsa_group_segment_fixed_size 0
		.amdhsa_private_segment_fixed_size 0
		.amdhsa_kernarg_size 408
		.amdhsa_user_sgpr_count 2
		.amdhsa_user_sgpr_dispatch_ptr 0
		.amdhsa_user_sgpr_queue_ptr 0
		.amdhsa_user_sgpr_kernarg_segment_ptr 1
		.amdhsa_user_sgpr_dispatch_id 0
		.amdhsa_user_sgpr_kernarg_preload_length 0
		.amdhsa_user_sgpr_kernarg_preload_offset 0
		.amdhsa_user_sgpr_private_segment_size 0
		.amdhsa_uses_dynamic_stack 0
		.amdhsa_enable_private_segment 0
		.amdhsa_system_sgpr_workgroup_id_x 1
		.amdhsa_system_sgpr_workgroup_id_y 0
		.amdhsa_system_sgpr_workgroup_id_z 0
		.amdhsa_system_sgpr_workgroup_info 0
		.amdhsa_system_vgpr_workitem_id 2
		.amdhsa_next_free_vgpr 256
		.amdhsa_next_free_sgpr 102
		.amdhsa_accum_offset 256
		.amdhsa_reserve_vcc 1
		.amdhsa_float_round_mode_32 0
		.amdhsa_float_round_mode_16_64 0
		.amdhsa_float_denorm_mode_32 3
		.amdhsa_float_denorm_mode_16_64 3
		.amdhsa_dx10_clamp 1
		.amdhsa_ieee_mode 1
		.amdhsa_fp16_overflow 0
		.amdhsa_tg_split 0
		.amdhsa_exception_fp_ieee_invalid_op 0
		.amdhsa_exception_fp_denorm_src 0
		.amdhsa_exception_fp_ieee_div_zero 0
		.amdhsa_exception_fp_ieee_overflow 0
		.amdhsa_exception_fp_ieee_underflow 0
		.amdhsa_exception_fp_ieee_inexact 0
		.amdhsa_exception_int_div_zero 0
	.end_amdhsa_kernel

; __global__ void __launch_bounds__(512, 2) mega(Params P) {
;   extern __shared__ __attribute__((aligned(16))) unsigned char shm[];
amdhsa.kernels:
  - .agpr_count:     0
    .args:
      - .offset:         0
        .size:           152
        .value_kind:     by_value
      - .offset:         152
        .size:           4
        .value_kind:     hidden_block_count_x
      - .offset:         156
        .size:           4
        .value_kind:     hidden_block_count_y
      - .offset:         160
        .size:           4
        .value_kind:     hidden_block_count_z
      - .offset:         164
        .size:           2
        .value_kind:     hidden_group_size_x
      - .offset:         166
        .size:           2
        .value_kind:     hidden_group_size_y
      - .offset:         168
        .size:           2
        .value_kind:     hidden_group_size_z
      - .offset:         170
        .size:           2
        .value_kind:     hidden_remainder_x
      - .offset:         172
        .size:           2
        .value_kind:     hidden_remainder_y
      - .offset:         174
        .size:           2
        .value_kind:     hidden_remainder_z
      - .offset:         192
        .size:           8
        .value_kind:     hidden_global_offset_x
      - .offset:         200
        .size:           8
        .value_kind:     hidden_global_offset_y
      - .offset:         208
        .size:           8
        .value_kind:     hidden_global_offset_z
      - .offset:         216
        .size:           2
        .value_kind:     hidden_grid_dims
      - .offset:         240
        .size:           8
        .value_kind:     hidden_multigrid_sync_arg
      - .offset:         272
        .size:           4
        .value_kind:     hidden_dynamic_lds_size
    .group_segment_fixed_size: 0
    .kernarg_segment_align: 8
    .kernarg_segment_size: 408
    .language:       OpenCL C
    .language_version:
      - 2
      - 0
    .max_flat_workgroup_size: 512
    .name:           _Z4mega6Params
    .private_segment_fixed_size: 0
    .sgpr_count:     108
    .sgpr_spill_count: 201
    .symbol:         _Z4mega6Params.kd
    .uniform_work_group_size: 1
    .uses_dynamic_stack: false
    .vgpr_count:     256
    .vgpr_spill_count: 0
    .wavefront_size: 64
